# G0 loads via scalar base + per-lane offsets (no VALU address math), ks1 fragment reads ahead of loads; first-item remap in phase 2b so critical SSD segments share CUs with lighter partners
# speedup vs baseline: 1.0247x; 1.0247x over previous
; #define LSTORE(S, buf_) { \
;       u16* dX_ = sX + (buf_) * 128 * 72; u16* dW_ = sW + (buf_) * 128 * 72; \
;       _Pragma("unroll") for (int i = 0; i < 4; ++i) { \
;         *(u32x4*)(dX_ + soff + i * 32 * 72) = rx[S][i]; \
;         *(u32x4*)(dW_ + soff + i * 32 * 72) = rw[S][i]; } }
; template <int MODE>
; PH void gemm_phase(const Params& p, int layer) {
;     ...
;     GLOAD(0, 0); GLOAD(1, 1);
;     LSTORE(0, 0);
;     __syncthreads();
.LBB0_168:
	s_nop 0
	v_add_u32_e32 v0, s6, v163
	v_ashrrev_i32_e32 v1, 31, v0
	v_readlane_b32 s6, v252, 55
	v_lshlrev_b64 v[0:1], 11, v[0:1]
	v_readlane_b32 s7, v252, 56
	s_nop 1
	v_lshl_add_u64 v[0:1], s[6:7], 0, v[0:1]
	v_readlane_b32 s6, v255, 23
	v_readlane_b32 s7, v255, 24
	v_lshl_add_u64 v[0:1], v[0:1], 0, v[160:161]
	s_mov_b32 s7, s3
	v_lshl_add_u64 v[12:13], v[0:1], 0, s[6:7]
	v_lshl_add_u32 v0, s2, 7, v163
	v_ashrrev_i32_e32 v1, 31, v0
	s_mov_b32 s2, s6
	v_lshlrev_b64 v[0:1], 11, v[0:1]
	v_writelane_b32 v255, s2, 23
	v_lshl_add_u64 v[0:1], s[0:1], 0, v[0:1]
	v_lshl_add_u64 v[0:1], v[0:1], 0, v[160:161]
	v_writelane_b32 v255, s3, 24
	s_mov_b32 s2, 0x10000
	v_add_co_u32_e32 v4, vcc, s2, v12
	v_lshl_add_u64 v[14:15], v[0:1], 0, s[6:7]
	s_nop 0
	v_addc_co_u32_e32 v5, vcc, 0, v13, vcc
	v_add_co_u32_e32 v6, vcc, s2, v14
	s_mov_b32 s2, 0x30000
	s_nop 0
	v_addc_co_u32_e32 v7, vcc, 0, v15, vcc
	v_add_co_u32_e32 v8, vcc, s66, v12
	global_load_dwordx4 v[16:19], v[12:13], off
	global_load_dwordx4 v[0:3], v[14:15], off
	v_addc_co_u32_e32 v9, vcc, 0, v13, vcc
	v_add_co_u32_e32 v10, vcc, s66, v14
	global_load_dwordx4 v[20:23], v[4:5], off
	s_nop 0
	global_load_dwordx4 v[4:7], v[6:7], off
	v_addc_co_u32_e32 v11, vcc, 0, v15, vcc
	v_add_co_u32_e32 v12, vcc, s2, v12
	global_load_dwordx4 v[24:27], v[8:9], off
	s_nop 0
	global_load_dwordx4 v[8:11], v[10:11], off
	v_addc_co_u32_e32 v13, vcc, 0, v13, vcc
	v_add_co_u32_e32 v14, vcc, s2, v14
	s_movk_i32 s2, 0x48
	s_nop 0
	v_addc_co_u32_e32 v15, vcc, 0, v15, vcc
	global_load_dwordx4 v[28:31], v[12:13], off
	s_nop 0
	global_load_dwordx4 v[12:15], v[14:15], off
	v_mad_u64_u32 v[68:69], s[6:7], v163, s2, v[64:65]
	v_readlane_b32 s6, v255, 0
	v_readlane_b32 s7, v255, 1
	v_lshl_add_u32 v203, v68, 1, 32
	v_lshrrev_b32_e32 v240, 4, v182
	v_and_b32_e32 v241, 7, v182
	v_and_b32_e32 v240, 7, v240
	v_xor_b32_e32 v240, v240, v241
	v_lshlrev_b32_e32 v240, 4, v240
	v_lshrrev_b32_e32 v241, 3, v182
	v_lshl_add_u32 v240, v241, 7, v240
	v_add_u32_e32 v203, 32, v240
	s_andn2_b64 vcc, exec, s[6:7]
	s_waitcnt vmcnt(15)
	ds_write_b128 v203, v[32:35]
	s_waitcnt vmcnt(14)
	ds_write_b128 v203, v[36:39] offset:36864
	s_waitcnt vmcnt(13)
	ds_write_b128 v203, v[40:43] offset:4096
	s_waitcnt vmcnt(12)
	ds_write_b128 v203, v[44:47] offset:40960
	s_waitcnt vmcnt(11)
	ds_write_b128 v203, v[48:51] offset:8192
	s_waitcnt vmcnt(10)
	ds_write_b128 v203, v[52:55] offset:45056
	s_waitcnt vmcnt(9)
	ds_write_b128 v203, v[56:59] offset:12288
	s_waitcnt vmcnt(8)
	ds_write_b128 v203, v[60:63] offset:49152
	s_waitcnt lgkmcnt(0)
	s_barrier
	s_cbranch_vccnz .LBB0_189
; DI int opaque_tid() { int t = threadIdx.x; asm volatile("" : "+v"(t)); return t; }
; template <int MODE>
; PH void gemm_phase(const Params& p, int layer) {
;     ...
;   const u16* X = (const u16*)(p.ws + (MODE == 0 ? WS_XB : WS_MIX));
;   const u16* W = (const u16*)(p.ws + (MODE == 0 ? WS_WIN : WS_WOUT)) + (size_t)layer * (MODE == 0 ? (size_t)NPAD * 1024 : (size_t)1024 * 2048);
;   u16* sX = (u16*)smem;
;   u16* sW = sX + 2 * 128 * 72;
;   const int tid = opaque_tid(), lane = tid & 63, w = tid >> 6, quad = lane >> 4, l15 = lane & 15;
;   const int wn = w >> 1, wm = w & 1;
;   const int ntiles = (MODE == 1) ? (128 * NTN) : (129 * NTN);
;   const int G = gridDim.x, bid = blockIdx.x;
;   const int off = ((G & 7) == 0) ? ((bid & 7) * (G >> 3) + (bid >> 3)) : bid;
;   if (off < ntiles) {
;     const int nt_b = (ntiles - off + G - 1) / G;
;     const int total = nt_b << LOGNK;
;     const int soff = (tid >> 3) * 72 + (tid & 7) * 8;
;     const int rowoff = tid >> 3, coloff = (tid & 7) * 8;
;     f32x4 acc[4][4];
;     u32x4 rx[2][4], rw[2][4];
	s_mul_i32 s6, s69, 0xc00
	s_mov_b32 s7, s3
	v_readlane_b32 s36, v252, 21
	s_lshl_b64 s[6:7], s[6:7], 2
	v_readlane_b32 s42, v252, 27
	v_readlane_b32 s48, v252, 33
	v_readlane_b32 s49, v252, 34
	v_readlane_b32 s50, v252, 35
	v_readlane_b32 s51, v252, 36
	v_and_b32_e32 v32, 15, v65
	v_bfe_u32 v33, v65, 6, 1
	s_mul_i32 s2, s69, 0x1400
	v_readlane_b32 s43, v252, 28
	s_add_u32 s8, s42, s6
	v_readlane_b32 s48, v252, 37
	v_lshl_or_b32 v36, v33, 6, v32
	v_cmp_eq_u32_e32 vcc, 0, v33
	v_mov_b32_e32 v33, 0xd800
	s_addc_u32 s9, s43, s7
	s_lshl_b64 s[6:7], s[2:3], 2
	v_readlane_b32 s52, v252, 41
	v_lshrrev_b32_e32 v35, 1, v65
	v_ashrrev_i32_e32 v205, 4, v65
	v_cndmask_b32_e32 v33, v33, v187, vcc
	s_mul_i32 s24, s69, 0x300
	s_mov_b32 s25, s3
	v_readlane_b32 s53, v252, 42
	s_add_u32 s15, s52, s6
	v_and_b32_e32 v35, 24, v35
	v_and_b32_e32 v37, 0xffffff80, v65
	v_add_u32_e32 v33, 32, v33
	v_cmp_gt_i32_e32 vcc, 48, v205
	v_readlane_b32 s44, v252, 29
	s_addc_u32 s18, s53, s7
	s_lshl_b64 s[6:7], s[24:25], 2
	v_add3_u32 v33, v33, v37, v35
	v_cndmask_b32_e32 v37, v188, v187, vcc
	v_cmp_gt_i32_e32 vcc, 32, v205
	s_mul_i32 s22, s69, 0x500
	s_mov_b32 s23, s3
	v_readlane_b32 s45, v252, 30
	s_add_u32 s19, s44, s6
	v_cndmask_b32_e32 v41, v188, v187, vcc
	v_cmp_gt_i32_e32 vcc, 16, v205
	v_readlane_b32 s54, v252, 43
	s_addc_u32 s21, s45, s7
	s_lshl_b64 s[6:7], s[22:23], 2
	v_ashrrev_i32_e32 v34, 1, v65
	v_lshl_add_u64 v[142:143], s[0:1], 0, v[160:161]
	s_mov_b32 s0, 0xfffffc0
	v_cndmask_b32_e32 v42, v188, v187, vcc
	v_cmp_gt_i32_e32 vcc, 0, v205
	v_readlane_b32 s55, v252, 44
	s_add_u32 s23, s54, s6
	v_and_or_b32 v40, v34, s0, v32
	v_cndmask_b32_e32 v43, v188, v187, vcc
	v_cmp_gt_i32_e32 vcc, -16, v205
	s_movk_i32 s0, 0xffd0
	s_mov_b32 s2, s24
	s_addc_u32 s24, s55, s7
	v_readlane_b32 s6, v252, 55
	v_and_b32_e32 v207, -8, v34
	s_movk_i32 s1, 0x110
	v_cndmask_b32_e32 v44, v188, v187, vcc
	v_cmp_gt_i32_e32 vcc, s0, v205
	s_movk_i32 s0, 0x43
	v_readlane_b32 s7, v252, 56
	v_and_b32_e32 v206, 0x78, v66
	v_mul_lo_u32 v38, v207, s1
	v_cndmask_b32_e32 v46, v188, v187, vcc
	v_cmp_gt_i32_e32 vcc, s0, v207
	v_mov_b32_e32 v47, 0x90d0
	v_mov_b32_e32 v48, 0x44d0
	v_lshl_add_u64 v[140:141], s[6:7], 0, v[160:161]
	v_add_u32_e32 v38, 32, v38
	v_cndmask_b32_e32 v47, v47, v48, vcc
	v_lshlrev_b32_e32 v160, 1, v206
	s_movk_i32 s0, 0x41
	v_lshl_add_u32 v39, v35, 1, 32
	v_mul_lo_u32 v35, v205, s1
	v_add3_u32 v208, v38, v47, v160
	v_add_u32_e32 v47, 0x45e0, v38
	v_add_u32_e32 v48, 0x91e0, v38
	v_cmp_gt_i32_e32 vcc, s0, v207
	v_add_u32_e32 v35, 32, v35
	v_add_u32_e32 v41, v35, v41
	v_cndmask_b32_e32 v47, v48, v47, vcc
	v_add_u32_e32 v209, v47, v160
	v_add_u32_e32 v47, 0x46f0, v38
	v_add_u32_e32 v48, 0x92f0, v38
	v_or_b32_e32 v212, 2, v207
	s_movk_i32 s0, 0x2200
	v_add_u32_e32 v42, v35, v42
	v_cndmask_b32_e32 v47, v48, v47, vcc
	v_cmp_gt_i32_e32 vcc, 64, v212
	v_or_b32_e32 v214, 4, v207
	v_add3_u32 v220, v41, v160, s0
	s_movk_i32 s0, 0x3300
	v_add_u32_e32 v43, v35, v43
	v_cndmask_b32_e32 v48, v188, v187, vcc
	v_cmp_gt_i32_e32 vcc, 64, v214
	v_or_b32_e32 v216, 6, v207
	v_add3_u32 v221, v42, v160, s0
	s_movk_i32 s0, 0x4400
	v_add_u32_e32 v44, v35, v44
	v_cndmask_b32_e32 v50, v188, v187, vcc
	v_cmp_gt_i32_e32 vcc, 64, v216
	v_add3_u32 v222, v43, v160, s0
	s_movk_i32 s0, 0x5500
	v_cndmask_b32_e32 v52, v188, v187, vcc
	v_cmp_gt_i32_e32 vcc, 64, v205
	v_add3_u32 v223, v44, v160, s0
	s_movk_i32 s0, 0xffe0
	v_cndmask_b32_e32 v53, v188, v187, vcc
	v_cmp_gt_i32_e32 vcc, s0, v205
	v_add_u32_e32 v37, v35, v37
	v_add_u32_e32 v45, 0x6600, v35
	v_or_b32_e32 v211, 1, v207
	v_add3_u32 v218, v35, v53, v160
	v_cndmask_b32_e32 v35, v188, v187, vcc
	v_cmp_gt_i32_e32 vcc, 64, v207
	v_add_u32_e32 v210, v47, v160
	v_mul_lo_u32 v47, v211, s1
	v_or_b32_e32 v213, 3, v207
	v_add3_u32 v224, v45, v35, v160
	v_cndmask_b32_e32 v35, v188, v187, vcc
	v_cmp_gt_i32_e32 vcc, 64, v211
	v_add_u32_e32 v47, 32, v47
	v_or_b32_e32 v215, 5, v207
	v_add3_u32 v226, v38, v35, v160
	v_cndmask_b32_e32 v35, v188, v187, vcc
	v_cmp_gt_i32_e32 vcc, 64, v213
	v_readlane_b32 s37, v252, 22
	v_readlane_b32 s38, v252, 23
	v_readlane_b32 s39, v252, 24
	v_readlane_b32 s40, v252, 25
	v_readlane_b32 s41, v252, 26
	v_add_u32_e32 v49, 0x220, v47
	v_or_b32_e32 v217, 7, v34
	v_add3_u32 v227, v47, v35, v160
	v_cndmask_b32_e32 v35, v188, v187, vcc
	v_cmp_gt_i32_e32 vcc, 64, v215
	v_writelane_b32 v255, s2, 41
	v_cmp_lt_i32_e64 s[36:37], 7, v34
	v_cmp_gt_i32_e64 s[38:39], 8, v34
	v_cmp_lt_i32_e64 s[40:41], -1, v34
	v_add_u32_e32 v51, 0x440, v47
	v_mul_lo_u32 v34, v217, s1
	v_add3_u32 v229, v49, v35, v160
	v_cndmask_b32_e32 v35, v188, v187, vcc
	v_cmp_gt_i32_e32 vcc, 64, v217
	v_writelane_b32 v255, s3, 42
	v_mul_lo_u32 v40, v40, s11
	v_mul_u32_u24_e32 v36, 0x90, v36
	v_mul_u32_u24_e32 v32, 0x110, v32
	v_add_u32_e32 v46, v45, v46
	v_add_u32_e32 v48, v47, v48
	v_add_u32_e32 v50, v49, v50
	v_add_u32_e32 v52, v51, v52
	v_add_u32_e32 v34, 32, v34
	s_movk_i32 s2, 0x1100
	v_add3_u32 v231, v51, v35, v160
	v_cndmask_b32_e32 v35, v188, v187, vcc
	v_add_u32_e32 v204, 0x9000, v203
	s_mov_b32 s25, 3
	v_lshl_add_u64 v[144:145], s[4:5], 0, v[160:161]
	v_add3_u32 v219, v37, v160, s2
	v_add3_u32 v225, v46, v160, s2
	v_add3_u32 v228, v48, v160, s1
	v_add3_u32 v230, v50, v160, s1
	v_add3_u32 v232, v52, v160, s1
	v_add3_u32 v160, v34, v35, v160
	v_add_u32_e32 v233, v39, v40
	v_add_u32_e32 v234, v39, v36
	v_and_b32_e32 v242, 15, v182
	v_lshrrev_b32_e32 v243, 1, v242
	v_bfe_u32 v244, v182, 4, 2
	v_and_b32_e32 v245, 3, v243
	v_xor_b32_e32 v244, v244, v245
	v_lshlrev_b32_e32 v244, 4, v244
	v_lshrrev_b32_e32 v245, 2, v243
	v_lshl_or_b32 v244, v245, 6, v244
	v_xor_b32_e32 v245, 64, v244
	v_lshrrev_b32_e32 v246, 7, v182
	v_lshl_or_b32 v246, v246, 6, v242
	v_bfe_u32 v247, v182, 6, 1
	v_lshl_or_b32 v247, v247, 6, v242
	v_lshlrev_b32_e32 v246, 7, v246
	v_lshlrev_b32_e32 v247, 7, v247
	v_add3_u32 v233, v246, v244, 32
	v_add3_u32 v240, v246, v245, 32
	v_add3_u32 v234, v247, v244, 32
	v_add3_u32 v241, v247, v245, 32
	v_readlane_b32 s72, v252, 55
	v_readlane_b32 s73, v252, 56
	s_mul_i32 s74, s69, 0x9c0000
	s_add_u32 s74, s94, s74
	s_addc_u32 s75, s95, 0
	v_lshrrev_b32_e32 v242, 3, v182
	v_and_b32_e32 v243, 7, v182
	v_lshlrev_b32_e32 v242, 11, v242
	v_lshl_add_u32 v242, v243, 4, v242
	v_add_u32_e32 v243, 0x10000, v242
	v_add_u32_e32 v244, 0x20000, v242
	v_add_u32_e32 v245, 0x30000, v242
	v_add_u32_e32 v235, v33, v32
	v_readlane_b32 s46, v252, 31
	v_readlane_b32 s47, v252, 32
	v_readlane_b32 s49, v252, 38
	v_readlane_b32 s50, v252, 39
	v_readlane_b32 s51, v252, 40
	v_readlane_b32 s56, v252, 45
	v_readlane_b32 s57, v252, 46
	v_readlane_b32 s58, v252, 47
	v_readlane_b32 s59, v252, 48
	v_readlane_b32 s60, v252, 49
	v_readlane_b32 s61, v252, 50
	v_readlane_b32 s62, v252, 51
	v_readlane_b32 s63, v252, 52
	s_branch .LBB0_173

; DI f32x4 mfma16(bf16x8 a, bf16x8 b, f32x4 c) { return __builtin_amdgcn_mfma_f32_16x16x32_bf16(a, b, c, 0, 0, 0); }
; template <int MODE>
; PH void gemm_phase(const Params& p, int layer) {
;     ...
;           const u16* cX = sX + (g & 1) * 128 * 72;
;           const u16* cW = sW + (g & 1) * 128 * 72;
;           u16* dX = sX + ((g + 1) & 1) * 128 * 72;
;           u16* dW = sW + ((g + 1) & 1) * 128 * 72;
; #pragma unroll
;           for (int ks = 0; ks < 2; ++ks) {
;             bf16x8 wf[4], xf[4];
; #pragma unroll
;             for (int i = 0; i < 4; ++i) {
;               wf[i] = ldfrag(cW, 72, wn * 64 + i * 16, ks * 32, lane);
;               xf[i] = ldfrag(cX, 72, wm * 64 + i * 16, ks * 32, lane);
;             }
;             __builtin_amdgcn_sched_barrier(0);
; #pragma unroll
;             for (int nt = 0; nt < 4; ++nt) {
; #pragma unroll
;               for (int mt = 0; mt < 4; ++mt) acc[nt][mt] = mfma16(wf[nt], xf[mt], acc[nt][mt]);
;               if (ks == 0) *(u32x4*)(dX + soff + nt * 32 * 72) = rx[(s + 1) & 1][nt];
;               else         *(u32x4*)(dW + soff + nt * 32 * 72) = rw[(s + 1) & 1][nt];
;               __builtin_amdgcn_sched_barrier(0);
;             }
;             if (ks == 0) { GLOAD(s, g + 2); __builtin_amdgcn_sched_barrier(0); }
;           }
.LBB0_175:
	s_add_i32 s13, s25, -1
	v_readlane_b32 s45, v254, 57
	s_min_i32 s2, s13, s45
	s_ashr_i32 s6, s2, 4
	s_mul_i32 s6, s6, s64
	v_readlane_b32 s44, v255, 8
	s_waitcnt vmcnt(9)
	ds_read_b128 v[96:99], v233 offset:36864
	s_waitcnt vmcnt(7)
	ds_read_b128 v[100:103], v233 offset:38912
	s_waitcnt vmcnt(3)
	ds_read_b128 v[104:107], v234
	ds_read_b128 v[108:111], v234 offset:2048
	s_waitcnt vmcnt(1)
	ds_read_b128 v[112:115], v233 offset:40960
	ds_read_b128 v[116:119], v233 offset:43008
	ds_read_b128 v[120:123], v234 offset:4096
	ds_read_b128 v[124:127], v234 offset:6144
	s_add_i32 s6, s6, s44
	s_mul_hi_i32 s22, s6, 0xd20d20d3
	s_add_i32 s22, s22, s6
	s_lshr_b32 s42, s22, 31
	s_ashr_i32 s22, s22, 8
	s_add_i32 s22, s22, s42
	s_mul_i32 s42, s22, 0x138
	s_sub_i32 s42, s6, s42
	s_lshr_b32 s43, s42, 3
	s_lshl_b32 s42, s42, 7
	s_lshl_b32 s22, s22, 10
	s_and_b32 s42, s42, 0x380
	s_lshl_b32 s2, s2, 7
	s_add_i32 s7, s6, 0xffffec80
	s_or_b32 s22, s42, s22
	s_and_b32 s2, s2, 0x780
	s_cmpk_lt_i32 s6, 0x1380
	s_cselect_b32 s76, s22, 0x4000
	s_cselect_b32 s78, s43, s7
	s_lshl_b32 s76, s76, 11
	s_lshl_b32 s78, s78, 18
	s_add_i32 s76, s76, s2
	s_add_i32 s78, s78, s2
	s_add_u32 s76, s72, s76
	s_addc_u32 s77, s73, 0
	s_add_u32 s78, s74, s78
	s_addc_u32 s79, s75, 0
	s_waitcnt lgkmcnt(5)
	v_mfma_f32_16x16x32_bf16 v[92:95], v[96:99], v[104:107], v[92:95]
	s_waitcnt vmcnt(7)
	ds_write_b128 v203, v[16:19] offset:18432
	s_waitcnt lgkmcnt(5)
	v_mfma_f32_16x16x32_bf16 v[88:91], v[96:99], v[108:111], v[88:91]
	s_waitcnt lgkmcnt(2)
	v_mfma_f32_16x16x32_bf16 v[84:87], v[96:99], v[120:123], v[84:87]
	s_waitcnt lgkmcnt(1)
	v_mfma_f32_16x16x32_bf16 v[16:19], v[96:99], v[124:127], v[80:83]
	v_mfma_f32_16x16x32_bf16 v[76:79], v[100:103], v[104:107], v[76:79]
	s_waitcnt vmcnt(5)
	ds_write_b128 v203, v[20:23] offset:22528
	v_mfma_f32_16x16x32_bf16 v[72:75], v[100:103], v[108:111], v[72:75]
	v_mfma_f32_16x16x32_bf16 v[68:71], v[100:103], v[120:123], v[68:71]
	v_mfma_f32_16x16x32_bf16 v[20:23], v[100:103], v[124:127], v[64:67]
	v_mfma_f32_16x16x32_bf16 v[60:63], v[112:115], v[104:107], v[60:63]
	s_waitcnt vmcnt(3)
	ds_write_b128 v203, v[24:27] offset:26624
	v_mfma_f32_16x16x32_bf16 v[56:59], v[112:115], v[108:111], v[56:59]
	v_mfma_f32_16x16x32_bf16 v[52:55], v[112:115], v[120:123], v[52:55]
	v_mfma_f32_16x16x32_bf16 v[24:27], v[112:115], v[124:127], v[48:51]
	v_mfma_f32_16x16x32_bf16 v[44:47], v[116:119], v[104:107], v[44:47]
	s_waitcnt vmcnt(1)
	ds_write_b128 v203, v[28:31] offset:30720
	v_mfma_f32_16x16x32_bf16 v[40:43], v[116:119], v[108:111], v[40:43]
	v_mfma_f32_16x16x32_bf16 v[36:39], v[116:119], v[120:123], v[36:39]
	v_mfma_f32_16x16x32_bf16 v[28:31], v[116:119], v[124:127], v[32:35]
	ds_read_b128 v[112:115], v240 offset:36864
	ds_read_b128 v[116:119], v240 offset:38912
	ds_read_b128 v[120:123], v241
	ds_read_b128 v[124:127], v241 offset:2048
	ds_read_b128 v[128:131], v240 offset:40960
	s_waitcnt vmcnt(8)
	ds_read_b128 v[132:135], v240 offset:43008
	ds_read_b128 v[136:139], v241 offset:4096
	ds_read_b128 v[146:149], v241 offset:6144
	global_load_dwordx4 v[32:35], v242, s[76:77]
	global_load_dwordx4 v[48:51], v242, s[78:79]
	global_load_dwordx4 v[64:67], v243, s[76:77]
	global_load_dwordx4 v[96:99], v243, s[78:79]
	global_load_dwordx4 v[80:83], v244, s[76:77]
	global_load_dwordx4 v[100:103], v244, s[78:79]
	global_load_dwordx4 v[104:107], v245, s[76:77]
	global_load_dwordx4 v[108:111], v245, s[78:79]
	s_waitcnt lgkmcnt(5)
	v_mfma_f32_16x16x32_bf16 v[92:95], v[112:115], v[120:123], v[92:95]
	ds_write_b128 v203, v[0:3] offset:55296
	s_waitcnt lgkmcnt(5)
	v_mfma_f32_16x16x32_bf16 v[88:91], v[112:115], v[124:127], v[88:91]
	s_waitcnt lgkmcnt(2)
	v_mfma_f32_16x16x32_bf16 v[84:87], v[112:115], v[136:139], v[84:87]
	s_waitcnt lgkmcnt(1)
	v_mfma_f32_16x16x32_bf16 v[0:3], v[112:115], v[146:149], v[16:19]
	v_mfma_f32_16x16x32_bf16 v[16:19], v[116:119], v[120:123], v[76:79]
	ds_write_b128 v203, v[4:7] offset:59392
	v_mfma_f32_16x16x32_bf16 v[72:75], v[116:119], v[124:127], v[72:75]
	v_mfma_f32_16x16x32_bf16 v[68:71], v[116:119], v[136:139], v[68:71]
	v_mfma_f32_16x16x32_bf16 v[4:7], v[116:119], v[146:149], v[20:23]
	v_mfma_f32_16x16x32_bf16 v[20:23], v[128:131], v[120:123], v[60:63]
	ds_write_b128 v203, v[8:11] offset:63488
	v_mfma_f32_16x16x32_bf16 v[56:59], v[128:131], v[124:127], v[56:59]
	v_mfma_f32_16x16x32_bf16 v[52:55], v[128:131], v[136:139], v[52:55]
	v_mfma_f32_16x16x32_bf16 v[8:11], v[128:131], v[146:149], v[24:27]
	v_mfma_f32_16x16x32_bf16 v[24:27], v[132:135], v[120:123], v[44:47]
	s_waitcnt vmcnt(8)
	ds_write_b128 v204, v[12:15] offset:30720
	v_mfma_f32_16x16x32_bf16 v[40:43], v[132:135], v[124:127], v[40:43]
	v_mfma_f32_16x16x32_bf16 v[36:39], v[132:135], v[136:139], v[36:39]
	v_mfma_f32_16x16x32_bf16 v[12:15], v[132:135], v[146:149], v[28:31]
	s_min_i32 s2, s25, s45
	s_ashr_i32 s6, s2, 4
	s_waitcnt lgkmcnt(0)
	s_barrier
; DI f32x4 mfma16(bf16x8 a, bf16x8 b, f32x4 c) { return __builtin_amdgcn_mfma_f32_16x16x32_bf16(a, b, c, 0, 0, 0); }
; template <int MODE>
; PH void gemm_phase(const Params& p, int layer) {
;     ...
;           const u16* cX = sX + (g & 1) * 128 * 72;
;           const u16* cW = sW + (g & 1) * 128 * 72;
;           u16* dX = sX + ((g + 1) & 1) * 128 * 72;
;           u16* dW = sW + ((g + 1) & 1) * 128 * 72;
; #pragma unroll
;           for (int ks = 0; ks < 2; ++ks) {
;             bf16x8 wf[4], xf[4];
; #pragma unroll
;             for (int i = 0; i < 4; ++i) {
;               wf[i] = ldfrag(cW, 72, wn * 64 + i * 16, ks * 32, lane);
;               xf[i] = ldfrag(cX, 72, wm * 64 + i * 16, ks * 32, lane);
;             }
;             __builtin_amdgcn_sched_barrier(0);
; #pragma unroll
;             for (int nt = 0; nt < 4; ++nt) {
; #pragma unroll
;               for (int mt = 0; mt < 4; ++mt) acc[nt][mt] = mfma16(wf[nt], xf[mt], acc[nt][mt]);
;               if (ks == 0) *(u32x4*)(dX + soff + nt * 32 * 72) = rx[(s + 1) & 1][nt];
;               else         *(u32x4*)(dW + soff + nt * 32 * 72) = rw[(s + 1) & 1][nt];
;               __builtin_amdgcn_sched_barrier(0);
;             }
;             if (ks == 0) { GLOAD(s, g + 2); __builtin_amdgcn_sched_barrier(0); }
;           }
;           __syncthreads();
	s_mul_i32 s6, s6, s64
	ds_read_b128 v[28:31], v233 offset:55296
	ds_read_b128 v[44:47], v233 offset:57344
	ds_read_b128 v[60:63], v234 offset:18432
	ds_read_b128 v[76:79], v234 offset:20480
	ds_read_b128 v[112:115], v233 offset:59392
	ds_read_b128 v[116:119], v233 offset:61440
	ds_read_b128 v[120:123], v234 offset:22528
	ds_read_b128 v[124:127], v234 offset:24576
	s_add_i32 s6, s6, s44
	s_mul_hi_i32 s22, s6, 0xd20d20d3
	s_add_i32 s22, s22, s6
	s_lshr_b32 s42, s22, 31
	s_ashr_i32 s22, s22, 8
	s_add_i32 s22, s22, s42
	s_mul_i32 s42, s22, 0x138
	s_sub_i32 s42, s6, s42
	s_lshr_b32 s43, s42, 3
	s_lshl_b32 s42, s42, 7
	s_lshl_b32 s22, s22, 10
	s_and_b32 s42, s42, 0x380
	s_lshl_b32 s2, s2, 7
	s_add_i32 s7, s6, 0xffffec80
	s_or_b32 s22, s42, s22
	s_and_b32 s2, s2, 0x780
	s_cmpk_lt_i32 s6, 0x1380
	s_cselect_b32 s76, s22, 0x4000
	s_cselect_b32 s78, s43, s7
	s_lshl_b32 s76, s76, 11
	s_lshl_b32 s78, s78, 18
	s_add_i32 s76, s76, s2
	s_add_i32 s78, s78, s2
	s_add_u32 s76, s72, s76
	s_addc_u32 s77, s73, 0
	s_add_u32 s78, s74, s78
	s_addc_u32 s79, s75, 0
	s_waitcnt lgkmcnt(5)
	v_mfma_f32_16x16x32_bf16 v[92:95], v[28:31], v[60:63], v[92:95]
	s_waitcnt vmcnt(7)
	ds_write_b128 v203, v[32:35]
	s_waitcnt lgkmcnt(5)
	v_mfma_f32_16x16x32_bf16 v[88:91], v[28:31], v[76:79], v[88:91]
	s_waitcnt lgkmcnt(2)
	v_mfma_f32_16x16x32_bf16 v[84:87], v[28:31], v[120:123], v[84:87]
	s_waitcnt lgkmcnt(1)
	v_mfma_f32_16x16x32_bf16 v[32:35], v[28:31], v[124:127], v[0:3]
	v_mfma_f32_16x16x32_bf16 v[128:131], v[44:47], v[60:63], v[16:19]
	s_waitcnt vmcnt(5)
	ds_write_b128 v203, v[64:67] offset:4096
	v_mfma_f32_16x16x32_bf16 v[72:75], v[44:47], v[76:79], v[72:75]
	v_mfma_f32_16x16x32_bf16 v[68:71], v[44:47], v[120:123], v[68:71]
	v_mfma_f32_16x16x32_bf16 v[44:47], v[44:47], v[124:127], v[4:7]
	v_mfma_f32_16x16x32_bf16 v[56:59], v[112:115], v[76:79], v[56:59]
	s_waitcnt vmcnt(3)
	ds_write_b128 v203, v[80:83] offset:8192
	v_mfma_f32_16x16x32_bf16 v[52:55], v[112:115], v[120:123], v[52:55]
	v_mfma_f32_16x16x32_bf16 v[132:135], v[112:115], v[60:63], v[20:23]
	v_mfma_f32_16x16x32_bf16 v[112:115], v[112:115], v[124:127], v[8:11]
	v_mfma_f32_16x16x32_bf16 v[40:43], v[116:119], v[76:79], v[40:43]
	s_waitcnt vmcnt(1)
	ds_write_b128 v203, v[104:107] offset:12288
	v_mfma_f32_16x16x32_bf16 v[36:39], v[116:119], v[120:123], v[36:39]
	v_mfma_f32_16x16x32_bf16 v[136:139], v[116:119], v[60:63], v[24:27]
	v_mfma_f32_16x16x32_bf16 v[104:107], v[116:119], v[124:127], v[12:15]
	ds_read_b128 v[60:63], v240 offset:55296
	ds_read_b128 v[64:67], v240 offset:57344
	ds_read_b128 v[116:119], v241 offset:18432
	ds_read_b128 v[120:123], v241 offset:20480
	ds_read_b128 v[124:127], v240 offset:59392
	ds_read_b128 v[146:149], v240 offset:61440
	ds_read_b128 v[150:153], v241 offset:22528
	ds_read_b128 v[154:157], v241 offset:24576
	global_load_dwordx4 v[16:19], v242, s[76:77]
	global_load_dwordx4 v[0:3], v242, s[78:79]
	global_load_dwordx4 v[20:23], v243, s[76:77]
	global_load_dwordx4 v[4:7], v243, s[78:79]
	global_load_dwordx4 v[24:27], v244, s[76:77]
	global_load_dwordx4 v[8:11], v244, s[78:79]
	global_load_dwordx4 v[28:31], v245, s[76:77]
	global_load_dwordx4 v[12:15], v245, s[78:79]
	s_waitcnt lgkmcnt(5)
	v_mfma_f32_16x16x32_bf16 v[92:95], v[60:63], v[116:119], v[92:95]
	ds_write_b128 v203, v[48:51] offset:36864
	s_waitcnt lgkmcnt(5)
	v_mfma_f32_16x16x32_bf16 v[88:91], v[60:63], v[120:123], v[88:91]
	s_waitcnt lgkmcnt(2)
	v_mfma_f32_16x16x32_bf16 v[84:87], v[60:63], v[150:153], v[84:87]
	s_waitcnt lgkmcnt(1)
	v_mfma_f32_16x16x32_bf16 v[80:83], v[60:63], v[154:157], v[32:35]
	v_mfma_f32_16x16x32_bf16 v[76:79], v[64:67], v[116:119], v[128:131]
	ds_write_b128 v203, v[96:99] offset:40960
	v_mfma_f32_16x16x32_bf16 v[72:75], v[64:67], v[120:123], v[72:75]
	v_mfma_f32_16x16x32_bf16 v[68:71], v[64:67], v[150:153], v[68:71]
	v_mfma_f32_16x16x32_bf16 v[64:67], v[64:67], v[154:157], v[44:47]
	v_mfma_f32_16x16x32_bf16 v[60:63], v[124:127], v[116:119], v[132:135]
	ds_write_b128 v203, v[100:103] offset:45056
	v_mfma_f32_16x16x32_bf16 v[56:59], v[124:127], v[120:123], v[56:59]
	v_mfma_f32_16x16x32_bf16 v[52:55], v[124:127], v[150:153], v[52:55]
	v_mfma_f32_16x16x32_bf16 v[48:51], v[124:127], v[154:157], v[112:115]
	v_mfma_f32_16x16x32_bf16 v[44:47], v[146:149], v[116:119], v[136:139]
	s_waitcnt vmcnt(8)
	ds_write_b128 v203, v[108:111] offset:49152
	v_mfma_f32_16x16x32_bf16 v[40:43], v[146:149], v[120:123], v[40:43]
	v_mfma_f32_16x16x32_bf16 v[36:39], v[146:149], v[150:153], v[36:39]
	v_mfma_f32_16x16x32_bf16 v[32:35], v[146:149], v[154:157], v[104:107]
	s_cmp_lg_u32 s1, 14
	s_waitcnt lgkmcnt(0)
	s_barrier
	s_cbranch_scc1 .LBB0_172
; DI unsigned pack2(float a, float b) { fl2_t v = {a, b}; return __builtin_bit_cast(unsigned, __builtin_convertvector(v, bf2_t)); }
; template <int MODE>
; PH void gemm_phase(const Params& p, int layer) {
;     ...
;           if (kt == NK - 1) {
;             int m0, n0; tile_coords(it * G + off, NTN, m0, n0);
;             if (MODE == 0) {
;               u16* PROJ = (u16*)(p.ws + WS_PROJ);
;               u16* eX = sX + (g & 1) * 128 * 72;
;               u16* eW = sW + (g & 1) * 128 * 72;
; #pragma unroll
;               for (int mt = 0; mt < 4; ++mt) {
;                 const int ml = mt * 16 + l15;
;                 u16* eb = (wm == 0 ? eX : eW) + ml * 136;
; #pragma unroll
;                 for (int nt = 0; nt < 4; ++nt) {
;                   const int nl = wn * 64 + nt * 16 + quad * 4;
;                   uint2 o; o.x = pack2(acc[nt][mt][0], acc[nt][mt][1]); o.y = pack2(acc[nt][mt][2], acc[nt][mt][3]);
;                   *(uint2*)(eb + nl) = o;
;                 }
;               }
;               __syncthreads();
; #pragma unroll
;               for (int i = 0; i < 8; ++i) {
;                 const int row = (tid >> 4) + 16 * i, ch = tid & 15;
;                 const u16* eb = (row < 64 ? eX + row * 136 : eW + (row - 64) * 136) + ch * 8;
;                 *(u32x4*)(PROJ + (size_t)(m0 + row) * NPAD + n0 + ch * 8) = *(const u32x4*)eb;
;               }
;               {
;                 const int tn_ = n0 >> 7;
;                 const bool is_lru = (tn_ >= 10) && (tn_ < 16), is_ssd = (tn_ >= 28) && (tn_ < 38);
;                 if ((is_lru || is_ssd) && m0 < MP) {
	s_lshr_b32 s0, s0, 4
	s_mul_i32 s0, s0, s64
	v_readlane_b32 s1, v255, 8
	s_add_i32 s0, s0, s1
	s_mul_hi_i32 s2, s0, 0xd20d20d3
	s_add_i32 s2, s2, s0
	s_lshr_b32 s6, s2, 31
	s_ashr_i32 s2, s2, 8
	v_cvt_pk_bf16_f32 v96, v92, v93
	v_cvt_pk_bf16_f32 v97, v94, v95
	v_cvt_pk_bf16_f32 v98, v76, v77
	v_cvt_pk_bf16_f32 v99, v78, v79
	s_add_i32 s2, s2, s6
	ds_write2_b64 v235, v[96:97], v[98:99] offset1:4
	v_cvt_pk_bf16_f32 v96, v60, v61
	v_cvt_pk_bf16_f32 v97, v62, v63
	v_cvt_pk_bf16_f32 v98, v44, v45
	v_cvt_pk_bf16_f32 v99, v46, v47
	s_mul_i32 s6, s2, 0x138
	ds_write2_b64 v235, v[96:97], v[98:99] offset0:8 offset1:12
	v_cvt_pk_bf16_f32 v96, v88, v89
	v_cvt_pk_bf16_f32 v97, v90, v91
	v_cvt_pk_bf16_f32 v98, v72, v73
	v_cvt_pk_bf16_f32 v99, v74, v75
	v_add_u32_e32 v100, 0x1000, v235
	s_sub_i32 s6, s0, s6
	ds_write2_b64 v100, v[96:97], v[98:99] offset0:32 offset1:36
	v_cvt_pk_bf16_f32 v96, v56, v57
	v_cvt_pk_bf16_f32 v97, v58, v59
	v_cvt_pk_bf16_f32 v98, v40, v41
	v_cvt_pk_bf16_f32 v99, v42, v43
	s_ashr_i32 s7, s6, 3
	s_lshl_b32 s6, s6, 7
	ds_write2_b64 v100, v[96:97], v[98:99] offset0:40 offset1:44
	v_cvt_pk_bf16_f32 v96, v84, v85
	v_cvt_pk_bf16_f32 v97, v86, v87
	v_cvt_pk_bf16_f32 v98, v68, v69
	v_cvt_pk_bf16_f32 v99, v70, v71
	v_add_u32_e32 v100, 0x2000, v235
	s_lshl_b32 s2, s2, 10
	s_and_b32 s6, s6, 0x380
	ds_write2_b64 v100, v[96:97], v[98:99] offset0:64 offset1:68
	v_cvt_pk_bf16_f32 v96, v52, v53
	v_cvt_pk_bf16_f32 v97, v54, v55
	v_cvt_pk_bf16_f32 v98, v36, v37
	v_cvt_pk_bf16_f32 v99, v38, v39
	s_add_i32 s1, s0, 0xffffec80
	s_or_b32 s2, s6, s2
	ds_write2_b64 v100, v[96:97], v[98:99] offset0:72 offset1:76
	v_cvt_pk_bf16_f32 v96, v80, v81
	v_cvt_pk_bf16_f32 v97, v82, v83
	v_cvt_pk_bf16_f32 v98, v64, v65
	v_cvt_pk_bf16_f32 v99, v66, v67
	v_add_u32_e32 v100, 0x3000, v235
	s_cmpk_lt_i32 s0, 0x1380
	ds_write2_b64 v100, v[96:97], v[98:99] offset0:96 offset1:100
	v_cvt_pk_bf16_f32 v96, v48, v49
	v_cvt_pk_bf16_f32 v97, v50, v51
	v_cvt_pk_bf16_f32 v98, v32, v33
	v_cvt_pk_bf16_f32 v99, v34, v35
	s_cselect_b32 s44, s7, s1
	ds_write2_b64 v100, v[96:97], v[98:99] offset0:104 offset1:108
	s_waitcnt lgkmcnt(0)
	s_barrier
	ds_read_b128 v[96:99], v218
	s_cselect_b32 s22, s2, 0x4000
	s_lshl_b32 s0, s44, 7
	s_ashr_i32 s1, s0, 31
	v_lshl_add_u64 v[100:101], s[0:1], 1, v[144:145]
	v_add_u32_e32 v104, s22, v205
	v_mad_i64_i32 v[102:103], s[6:7], v104, s97, v[100:101]
	s_waitcnt lgkmcnt(0)
	global_store_dwordx4 v[102:103], v[96:99], off
	ds_read_b128 v[96:99], v219
	v_add_u32_e32 v102, 16, v104
	v_mad_i64_i32 v[102:103], s[6:7], v102, s97, v[100:101]
	s_add_i32 s1, s44, -10
	s_waitcnt lgkmcnt(0)
	global_store_dwordx4 v[102:103], v[96:99], off
	ds_read_b128 v[96:99], v220
	v_add_u32_e32 v102, 32, v104
	v_mad_i64_i32 v[102:103], s[6:7], v102, s97, v[100:101]
	s_cmp_lt_u32 s1, 6
	s_waitcnt lgkmcnt(0)
	global_store_dwordx4 v[102:103], v[96:99], off
	ds_read_b128 v[96:99], v221
	v_add_u32_e32 v102, 48, v104
	v_mad_i64_i32 v[102:103], s[6:7], v102, s97, v[100:101]
	s_cselect_b64 s[42:43], -1, 0
	s_waitcnt lgkmcnt(0)
	global_store_dwordx4 v[102:103], v[96:99], off
	ds_read_b128 v[96:99], v222
	v_add_u32_e32 v102, 64, v104
	v_mad_i64_i32 v[102:103], s[6:7], v102, s97, v[100:101]
	s_cmp_gt_u32 s1, 5
	s_waitcnt lgkmcnt(0)
	global_store_dwordx4 v[102:103], v[96:99], off
	ds_read_b128 v[96:99], v223
	v_add_u32_e32 v102, 0x50, v104
	v_mad_i64_i32 v[102:103], s[6:7], v102, s97, v[100:101]
	s_waitcnt lgkmcnt(0)
	global_store_dwordx4 v[102:103], v[96:99], off
	ds_read_b128 v[96:99], v224
	v_add_u32_e32 v102, 0x60, v104
	v_mad_i64_i32 v[102:103], s[6:7], v102, s97, v[100:101]
	s_waitcnt lgkmcnt(0)
	global_store_dwordx4 v[102:103], v[96:99], off
	v_add_u32_e32 v102, 0x70, v104
	v_mad_i64_i32 v[100:101], s[6:7], v102, s97, v[100:101]
	s_cselect_b64 s[6:7], -1, 0
	s_sub_i32 s1, s44, 28
	s_cmp_gt_u32 s1, 9
	s_cselect_b64 s[44:45], -1, 0
	ds_read_b128 v[96:99], v225
	s_and_b64 s[6:7], s[6:7], s[44:45]
	s_cmpk_gt_i32 s22, 0x3fff
	s_cselect_b64 s[44:45], -1, 0
	s_or_b64 s[6:7], s[6:7], s[44:45]
	s_and_b64 vcc, exec, s[6:7]
	s_waitcnt lgkmcnt(0)
	global_store_dwordx4 v[100:101], v[96:99], off
	s_cbranch_vccnz .LBB0_171
; template <int MODE>
; PH void gemm_phase(const Params& p, int layer) {
;     ...
;                   const int o = tid & 15, rbase = (tid >> 4) * 8;
;                   const int nch = is_lru ? 768 : 1280;
;                   const int chn = (is_lru ? (n0 - C_XL) : (n0 - C_XBC)) + o * 8;
;                   const float* cw = (is_lru ? (p.in[11] + layer * 4 * 768) : (p.in[18] + layer * 4 * 1280)) + chn;
;                   const float* cb = (is_lru ? (p.in[12] + layer * 768) : (p.in[19] + layer * 1280)) + chn;
;                   u16* dst = (u16*)(p.ws + (is_lru ? WS_XL : WS_XBC)) + chn;
;                   float w0[8], w1[8], w2[8], w3[8], bs[8];
; #pragma unroll
;                   for (int h = 0; h < 2; ++h) {
;                     const float4 a0 = *(const float4*)(cw + 0 * nch + 4 * h), a1 = *(const float4*)(cw + 1 * nch + 4 * h);
;                     const float4 a2 = *(const float4*)(cw + 2 * nch + 4 * h), a3 = *(const float4*)(cw + 3 * nch + 4 * h);
;                     const float4 b4 = *(const float4*)(cb + 4 * h);
;                     w0[4 * h] = a0.x; w0[4 * h + 1] = a0.y; w0[4 * h + 2] = a0.z; w0[4 * h + 3] = a0.w;
;                     w1[4 * h] = a1.x; w1[4 * h + 1] = a1.y; w1[4 * h + 2] = a1.z; w1[4 * h + 3] = a1.w;
;                     w2[4 * h] = a2.x; w2[4 * h + 1] = a2.y; w2[4 * h + 2] = a2.z; w2[4 * h + 3] = a2.w;
;                     w3[4 * h] = a3.x; w3[4 * h + 1] = a3.y; w3[4 * h + 2] = a3.z; w3[4 * h + 3] = a3.w;
;                     bs[4 * h] = b4.x; bs[4 * h + 1] = b4.y; bs[4 * h + 2] = b4.z; bs[4 * h + 3] = b4.w;
;                   }
;                   float xa[8], xb[8], xc[8], xd[8], yv[8];
; #pragma unroll
;                   for (int c = 0; c < 8; ++c) { xa[c] = 0.f; xb[c] = 0.f; xc[c] = 0.f; }
;                   if (rbase >= 8) {
;                     const int r1 = rbase - 3, r2 = rbase - 2, r3 = rbase - 1;
;                     unpack8(*(const uint4*)((r1 < 64 ? eX + r1 * 136 : eW + (r1 - 64) * 136) + o * 8), xa);
;                     unpack8(*(const uint4*)((r2 < 64 ? eX + r2 * 136 : eW + (r2 - 64) * 136) + o * 8), xb);
;                     unpack8(*(const uint4*)((r3 < 64 ? eX + r3 * 136 : eW + (r3 - 64) * 136) + o * 8), xc);
;                   }
	s_and_b64 s[6:7], s[42:43], exec
	s_movk_i32 s1, 0x300
	s_cselect_b32 s44, s1, 0x500
	s_movk_i32 s1, 0xfb00
	s_cselect_b32 s1, s1, 0xfffff200
	s_add_i32 s1, s1, s0
	v_or_b32_e32 v146, s1, v206
	s_and_b64 s[0:1], s[42:43], exec
	v_ashrrev_i32_e32 v147, 31, v146
	s_cselect_b32 s1, s9, s18
	s_cselect_b32 s0, s8, s15
	v_lshlrev_b64 v[96:97], 2, v[146:147]
	v_lshl_add_u64 v[100:101], s[0:1], 0, v[96:97]
	s_cselect_b32 s1, s21, s24
	s_cselect_b32 s0, s19, s23
	s_lshl_b32 s2, s44, 2
	v_lshl_add_u64 v[104:105], v[100:101], 0, s[2:3]
	s_lshl_b32 s2, s44, 3
	v_lshl_add_u64 v[106:107], v[100:101], 0, s[2:3]
	s_mul_i32 s2, s44, 12
	v_lshl_add_u64 v[132:133], s[0:1], 0, v[96:97]
	v_lshl_add_u64 v[112:113], v[100:101], 0, s[2:3]
	global_load_dwordx4 v[96:99], v[100:101], off offset:16
	global_load_dwordx4 v[116:119], v[100:101], off
	s_nop 0
	global_load_dwordx4 v[100:103], v[104:105], off offset:16
	global_load_dwordx4 v[120:123], v[104:105], off
	global_load_dwordx4 v[108:111], v[106:107], off offset:16
	global_load_dwordx4 v[128:131], v[106:107], off
	s_nop 0
	global_load_dwordx4 v[104:107], v[112:113], off offset:16
	global_load_dwordx4 v[124:127], v[112:113], off
	s_nop 0
	global_load_dwordx4 v[112:115], v[132:133], off offset:16
	s_nop 0
	global_load_dwordx4 v[132:135], v[132:133], off
	v_mov_b32_e32 v180, 0
	v_mov_b32_e32 v181, v180
	v_mov_b32_e32 v172, v180
	v_mov_b32_e32 v173, v180
	v_mov_b32_e32 v164, v180
	v_mov_b32_e32 v165, v180
	v_mov_b32_e32 v152, v180
	v_mov_b32_e32 v153, v180
	v_mov_b32_e32 v174, v180
	v_mov_b32_e32 v175, v180
	v_mov_b32_e32 v168, v180
	v_mov_b32_e32 v169, v180
	v_mov_b32_e32 v156, v180
	v_mov_b32_e32 v157, v180
	v_mov_b32_e32 v148, v180
	v_mov_b32_e32 v149, v180
	v_mov_b32_e32 v150, v180
	v_mov_b32_e32 v151, v180
	v_mov_b32_e32 v158, v180
	v_mov_b32_e32 v159, v180
	v_mov_b32_e32 v170, v180
	v_mov_b32_e32 v171, v180
	v_mov_b32_e32 v178, v180
	v_mov_b32_e32 v179, v180
	s_and_saveexec_b64 s[0:1], s[36:37]
	s_cbranch_execz .LBB0_179
	ds_read_b128 v[136:139], v208
	ds_read_b128 v[152:155], v209
	s_waitcnt lgkmcnt(1)
	v_lshlrev_b32_e32 v178, 16, v136
	v_and_b32_e32 v179, 0xffff0000, v136
	v_lshlrev_b32_e32 v170, 16, v137
	v_and_b32_e32 v171, 0xffff0000, v137
	v_lshlrev_b32_e32 v158, 16, v138
	v_and_b32_e32 v159, 0xffff0000, v138
	v_lshlrev_b32_e32 v150, 16, v139
	v_and_b32_e32 v151, 0xffff0000, v139
	ds_read_b128 v[136:139], v210
	s_waitcnt lgkmcnt(1)
	v_lshlrev_b32_e32 v174, 16, v152
	v_and_b32_e32 v175, 0xffff0000, v152
	v_lshlrev_b32_e32 v168, 16, v153
	v_and_b32_e32 v169, 0xffff0000, v153
	v_lshlrev_b32_e32 v156, 16, v154
	v_and_b32_e32 v157, 0xffff0000, v154
	v_lshlrev_b32_e32 v148, 16, v155
	v_and_b32_e32 v149, 0xffff0000, v155
	s_waitcnt lgkmcnt(0)
	v_lshlrev_b32_e32 v180, 16, v136
	v_and_b32_e32 v181, 0xffff0000, v136
	v_lshlrev_b32_e32 v172, 16, v137
	v_and_b32_e32 v173, 0xffff0000, v137
	v_lshlrev_b32_e32 v164, 16, v138
	v_and_b32_e32 v165, 0xffff0000, v138
	v_lshlrev_b32_e32 v152, 16, v139
	v_and_b32_e32 v153, 0xffff0000, v139

; __global__ void __launch_bounds__(256, 2) mega(Params p) {
;     ...
;     for (int rep = 0; rep < REP_2B; ++rep) {
;       bool first = true;
;       for (;;) {
;         int it;
;         if (first) { it = (int)blockIdx.x; first = false; }
;         else it = next_item(ctr + layer * 2 + 1 + 8 * rep, &slot) + (int)gridDim.x;
;         if (rep > 0) { it += PROBE_2B_LO; if (it >= PROBE_2B_HI) break; }
;         if (it >= 288 + 192 + 24 + 256 + 1536) break;
;         it = (it < 192) ? (it + 384) : ((it < 480) ? (it - 192) : ((it < 504) ? (it + 608) : ((it < 760) ? (it + 328) : (it + 352))));
.LBB0_354:
	s_or_b64 exec, exec, s[0:1]
	s_mul_i32 s0, s69, 12
	v_writelane_b32 v255, s0, 51
	v_readlane_b32 s2, v252, 0
	s_waitcnt lgkmcnt(0)
	s_barrier
	s_cmp_lt_u32 s2, 192
	s_cbranch_scc1 .Lmap2b_done
	s_cmp_lt_u32 s2, 224
	s_cbranch_scc0 .Lmap2b_a
	s_add_i32 s2, s2, 128
	s_branch .Lmap2b_done
.Lmap2b_a:
	s_cmp_lt_u32 s2, 256
	s_cbranch_scc0 .Lmap2b_b
	s_add_i32 s2, s2, 224
	s_branch .Lmap2b_done
.Lmap2b_b:
	s_cmp_lt_u32 s2, 320
	s_cbranch_scc0 .Lmap2b_c
	s_add_i32 s2, s2, 128
	s_branch .Lmap2b_done
.Lmap2b_c:
	s_cmp_lt_u32 s2, 448
	s_cbranch_scc0 .Lmap2b_d
	s_add_i32 s2, s2, 0xffffff80
	s_branch .Lmap2b_done
.Lmap2b_d:
	s_cmp_lt_u32 s2, 480
	s_cbranch_scc0 .Lmap2b_done
	s_add_i32 s2, s2, 0xffffffa0
.Lmap2b_done:
	s_branch .LBB0_358
.LBB0_355:
	s_or_b64 exec, exec, s[6:7]
	s_waitcnt vmcnt(0)
	v_readfirstlane_b32 s2, v1
	s_nop 1
	v_add_u32_e32 v0, s2, v0
	ds_write_b32 v161, v0 offset:16
